# prep section A: wave 0's four input loads (ca, cb, dt_bias, a_log) prefetched one item ahead from the section-D code of the previous item (preheader for the first item)
# speedup vs baseline: 1.0613x; 1.0039x over previous
.LBB0_307:
	s_cmp_eq_u32 s101, 1
	s_cbranch_scc1 .Lgsync_ret
	s_or_b64 exec, exec, s[0:1]
	s_xor_b64 s[0:1], s[2:3], -1
	v_writelane_b32 v252, s0, 10
	s_mov_b64 s[10:11], s[70:71]
	s_waitcnt lgkmcnt(0)
	v_writelane_b32 v252, s1, 11
	v_readlane_b32 s0, v249, 33
	v_readlane_b32 s1, v249, 34
	s_andn2_b64 vcc, exec, s[0:1]
	s_barrier
	v_cndmask_b32_e64 v1, 0, 1, s[0:1]
	v_cmp_ne_u32_e64 s[2:3], 1, v1
	s_nop 1
	v_writelane_b32 v252, s2, 12
	s_nop 1
	v_writelane_b32 v252, s3, 13
	s_cbranch_vccnz .LBB0_550
	s_add_u32 s12, s10, 0xb400000
	s_addc_u32 s13, s11, 0
	s_add_u32 s14, s10, 0x11400000
	v_readlane_b32 s16, v251, 14
	v_readlane_b32 s18, v250, 50
	v_readlane_b32 s20, v250, 46
	s_addc_u32 s15, s11, 0
	v_readlane_b32 s17, v251, 15
	v_readlane_b32 s19, v250, 51
	v_readlane_b32 s21, v250, 47
	v_readlane_b32 s22, v250, 45
	s_mov_b32 s23, s72
	v_readfirstlane_b32 s0, v206
	s_cmp_lt_u32 s0, 64
	s_cbranch_scc0 .Lpa_skip0
	s_ashr_i32 s0, s72, 10
	s_lshl_b32 s0, s0, 13
	s_and_b32 s1, s72, 0x7f
	s_lshl_b32 s1, s1, 6
	s_add_u32 s0, s0, s1
	v_and_b32_e32 v4, 63, v206
	v_add_u32_e32 v4, s0, v4
	v_lshlrev_b32_e32 v4, 6, v4
	s_bfe_u32 s1, s72, 0x30007
	s_lshl_b32 s1, s1, 2
	v_add_u32_e32 v4, s1, v4
	v_mov_b32_e32 v5, s1
	v_readlane_b32 s2, v251, 53
	v_readlane_b32 s3, v251, 54
	v_readlane_b32 s4, v251, 55
	v_readlane_b32 s5, v251, 56
	global_load_dword v242, v4, s[14:15]
	global_load_dword v243, v4, s[14:15] offset:32
	s_nop 2
	global_load_dword v244, v5, s[2:3]
	global_load_dword v245, v5, s[4:5]
	s_waitcnt vmcnt(0)
.Lpa_skip0:
	s_branch .LBB0_310

.LBB0_312:
	s_ashr_i32 s2, s23, 10
	v_and_b32_e32 v134, 63, v135
	s_ashr_i32 s3, s2, 31
	s_bfe_u32 s6, s23, 0x30007
	s_lshl_b64 s[4:5], s[2:3], 13
	s_and_b32 s7, s22, 0x1fc0
	s_andn2_b64 vcc, exec, s[0:1]
	v_cmp_gt_u32_e64 s[0:1], 32, v134
	s_cbranch_vccnz .LBB0_316
	v_or_b32_e32 v1, s7, v134
	v_or_b32_e32 v2, s4, v1
	v_mov_b32_e32 v3, s5
	v_lshlrev_b64 v[2:3], 6, v[2:3]
	v_lshl_add_u64 v[2:3], s[14:15], 0, v[2:3]
	s_lshl_b32 s52, s6, 2
	v_readlane_b32 s2, v251, 53
	v_lshl_add_u64 v[2:3], v[2:3], 0, s[52:53]
	v_mov_b32_e32 v8, s52
	v_readlane_b32 s3, v251, 54
	v_add_u32_e32 v10, -1, v211
	v_add_u32_e32 v11, -2, v211
	v_add_u32_e32 v12, -4, v211
	v_add_u32_e32 v13, -8, v211
	v_readlane_b32 s2, v251, 55
	v_readlane_b32 s3, v251, 56
	s_nop 4
	s_nop 0
	v_and_b32_e32 v2, 64, v211
	v_cmp_lt_i32_e32 vcc, v10, v2
	v_add_u32_e32 v14, -16, v211
	v_subrev_u32_e32 v15, 32, v211
	v_cndmask_b32_e32 v10, v10, v211, vcc
	v_cmp_lt_i32_e32 vcc, v11, v2
	s_mov_b32 s2, 0x3f317217
	v_lshlrev_b32_e32 v10, 2, v10
	v_cndmask_b32_e32 v11, v11, v211, vcc
	v_cmp_lt_i32_e32 vcc, v12, v2
	v_lshlrev_b32_e32 v11, 2, v11
	v_lshl_add_u32 v16, v134, 2, 0
	v_cndmask_b32_e32 v12, v12, v211, vcc
	v_cmp_lt_i32_e32 vcc, v13, v2
	v_lshlrev_b32_e32 v12, 2, v12
	v_add_u32_e32 v17, 0x20500, v16
	v_cndmask_b32_e32 v13, v13, v211, vcc
	v_cmp_lt_i32_e32 vcc, v14, v2
	v_lshlrev_b32_e32 v13, 2, v13
	v_add_u32_e32 v16, 0x20600, v16
	v_cndmask_b32_e32 v14, v14, v211, vcc
	v_cmp_lt_i32_e32 vcc, v15, v2
	s_waitcnt vmcnt(8)
	v_mov_b32_e32 v1, v242
	v_mov_b32_e32 v9, v244
	v_mov_b32_e32 v8, v245
	v_mov_b32_e32 v3, v243
	v_add_f32_e32 v1, v1, v9
	v_mul_f32_e32 v9, 0x3fb8aa3b, v1
	v_exp_f32_e32 v9, v9
	v_cndmask_b32_e32 v15, v15, v211, vcc
	v_mul_f32_e32 v8, 0x3fb8aa3b, v8
	v_exp_f32_e32 v8, v8
	v_add_f32_e32 v9, 1.0, v9
	v_cmp_gt_f32_e32 vcc, s51, v9
	v_mul_f32_e32 v3, 0xbfb8aa3b, v3
	v_exp_f32_e32 v3, v3
	v_cndmask_b32_e64 v18, 0, 32, vcc
	v_ldexp_f32 v9, v9, v18
	v_log_f32_e32 v9, v9
	v_cndmask_b32_e32 v18, 0, v213, vcc
	v_add_f32_e32 v3, 1.0, v3
	v_mul_f32_e32 v19, 0x3f317217, v9
	v_fma_f32 v19, v9, s2, -v19
	v_fmac_f32_e32 v19, 0x3377d1cf, v9
	s_mov_b32 s2, 0x7f800000
	v_fmac_f32_e32 v19, 0x3f317217, v9
	v_cmp_lt_f32_e64 vcc, |v9|, s2
	s_mov_b32 s2, 0x41a00000
	s_nop 0
	v_cndmask_b32_e32 v9, v9, v19, vcc
	v_sub_f32_e32 v9, v9, v18
	v_cmp_lt_f32_e32 vcc, s2, v1
	s_nop 1
	v_cndmask_b32_e32 v1, v9, v1, vcc
	v_mul_f32_e64 v9, v1, -v8
	ds_bpermute_b32 v10, v10, v9
	v_cmp_eq_u32_e32 vcc, 0, v134
	s_waitcnt lgkmcnt(0)
	v_fma_f32 v1, v1, -v8, v10
	v_cndmask_b32_e32 v1, v1, v9, vcc
	ds_bpermute_b32 v8, v11, v1
	v_cmp_gt_u32_e32 vcc, 2, v134
	v_div_scale_f32 v11, s[2:3], v3, v3, 1.0
	v_cmp_gt_u32_e64 s[2:3], 8, v134
	s_waitcnt lgkmcnt(0)
	v_add_f32_e32 v8, v1, v8
	v_cndmask_b32_e32 v1, v8, v1, vcc
	ds_bpermute_b32 v8, v12, v1
	v_cmp_gt_u32_e32 vcc, 4, v134
	v_lshlrev_b32_e32 v9, 2, v14
	v_rcp_f32_e32 v12, v11
	v_lshlrev_b32_e32 v10, 2, v15
	s_waitcnt lgkmcnt(0)
	v_add_f32_e32 v8, v1, v8
	v_cndmask_b32_e32 v1, v8, v1, vcc
	ds_bpermute_b32 v8, v13, v1
	v_fma_f32 v14, -v11, v12, 1.0
	v_div_scale_f32 v13, vcc, 1.0, v3, 1.0
	v_fmac_f32_e32 v12, v14, v12
	s_waitcnt lgkmcnt(0)
	v_add_f32_e32 v8, v1, v8
	v_cndmask_b32_e64 v1, v8, v1, s[2:3]
	ds_bpermute_b32 v8, v9, v1
	v_cmp_gt_u32_e64 s[2:3], 16, v134
	v_mul_f32_e32 v9, v13, v12
	v_fma_f32 v14, -v11, v9, v13
	v_fmac_f32_e32 v9, v14, v12
	s_waitcnt lgkmcnt(0)
	v_add_f32_e32 v8, v1, v8
	v_cndmask_b32_e64 v8, v8, v1, s[2:3]
	ds_bpermute_b32 v1, v10, v8
	v_fma_f32 v11, -v11, v9, v13
	v_div_fmas_f32 v9, v11, v12, v9
	v_div_fixup_f32 v3, v9, v3, 1.0
	ds_write_b32 v16, v3
	s_waitcnt lgkmcnt(1)
	v_add_f32_e32 v1, v8, v1
	v_cndmask_b32_e64 v3, v1, v8, s[0:1]
	v_cmp_eq_u32_e32 vcc, 63, v134
	ds_write_b32 v17, v3
	s_and_saveexec_b64 s[0:1], vcc
	s_cbranch_execz .LBB0_315
	v_mul_f32_e32 v1, 0x3fb8aa3b, v1
	v_exp_f32_e32 v1, v1
	s_add_u32 s2, s10, s20
	s_addc_u32 s3, s11, s21
	global_store_dword v0, v1, s[2:3]

.Lpd_inv:
	s_add_i32 s36, s23, s74
	s_ashr_i32 s37, s36, 10
	s_lshl_b32 s37, s37, 13
	s_and_b32 s38, s36, 0x7f
	s_lshl_b32 s38, s38, 6
	s_add_u32 s37, s37, s38
	v_add_u32_e32 v4, s37, v134
	v_lshlrev_b32_e32 v4, 6, v4
	s_bfe_u32 s38, s36, 0x30007
	s_lshl_b32 s38, s38, 2
	v_add_u32_e32 v4, s38, v4
	v_mov_b32_e32 v5, s38
	v_readlane_b32 s40, v251, 53
	v_readlane_b32 s41, v251, 54
	v_readlane_b32 s44, v251, 55
	v_readlane_b32 s45, v251, 56
	global_load_dword v242, v4, s[14:15]
	global_load_dword v243, v4, s[14:15] offset:32
	s_nop 2
	global_load_dword v244, v5, s[40:41]
	global_load_dword v245, v5, s[44:45]
	v_lshrrev_b32_e32 v2, 4, v135
	v_mul_u32_u24_e32 v2, 0x1140, v2
	ds_read_b128 v[136:139], v2 offset:52224
	ds_read_b128 v[140:143], v2 offset:52240
	ds_read_b128 v[144:147], v2 offset:52256
	ds_read_b128 v[148:151], v2 offset:52272
	ds_read_b128 v[168:171], v2 offset:52496
	ds_read_b128 v[172:175], v2 offset:52512
	ds_read_b128 v[176:179], v2 offset:52528
	ds_read_b128 v[184:187], v2 offset:52544
	ds_read_b128 v[188:191], v2 offset:52768
	ds_read_b128 v[192:195], v2 offset:52784
	ds_read_b128 v[196:199], v2 offset:52800
	ds_read_b128 v[200:203], v2 offset:52816
	ds_read_b128 v[234:237], v2 offset:53056
	ds_read_b128 v[238:241], v2 offset:53072
	ds_read_b128 v[30:33], v2 offset:53088
	ds_read_b128 v[34:37], v2 offset:53328
	ds_read_b128 v[42:45], v2 offset:53344
	ds_read_b128 v[160:163], v2 offset:53360
	v_cmp_eq_u32_e64 s[0:1], 0, v1
	v_cmp_eq_u32_e64 s[2:3], 1, v1
	v_cmp_eq_u32_e64 s[4:5], 2, v1
	v_cmp_eq_u32_e64 s[6:7], 3, v1
	v_cmp_eq_u32_e64 s[28:29], 4, v1
	v_cmp_eq_u32_e64 s[30:31], 5, v1
	v_cmp_eq_u32_e64 s[32:33], 6, v1
	v_cmp_eq_u32_e64 s[34:35], 7, v1
	v_cndmask_b32_e64 v8, 0, 1.0, s[0:1]
	v_cndmask_b32_e64 v9, 0, 1.0, s[2:3]
	v_cndmask_b32_e64 v10, 0, 1.0, s[4:5]
	v_cndmask_b32_e64 v11, 0, 1.0, s[6:7]
	v_cndmask_b32_e64 v12, 0, 1.0, s[28:29]
	v_cndmask_b32_e64 v13, 0, 1.0, s[30:31]
	v_cndmask_b32_e64 v14, 0, 1.0, s[32:33]
	v_cndmask_b32_e64 v15, 0, 1.0, s[34:35]
	v_cmp_eq_u32_e64 s[0:1], 8, v1
	v_cmp_eq_u32_e64 s[2:3], 9, v1
	v_cmp_eq_u32_e64 s[4:5], 10, v1
	v_cmp_eq_u32_e64 s[6:7], 11, v1
	v_cmp_eq_u32_e64 s[28:29], 12, v1
	v_cmp_eq_u32_e64 s[30:31], 13, v1
	v_cmp_eq_u32_e64 s[32:33], 14, v1
	v_cmp_eq_u32_e64 s[34:35], 15, v1
	v_cndmask_b32_e64 v16, 0, 1.0, s[0:1]
	v_cndmask_b32_e64 v17, 0, 1.0, s[2:3]
	v_cndmask_b32_e64 v18, 0, 1.0, s[4:5]
	v_cndmask_b32_e64 v19, 0, 1.0, s[6:7]
	v_cndmask_b32_e64 v20, 0, 1.0, s[28:29]
	v_cndmask_b32_e64 v21, 0, 1.0, s[30:31]
	v_cndmask_b32_e64 v22, 0, 1.0, s[32:33]
	v_cndmask_b32_e64 v23, 0, 1.0, s[34:35]
	v_readlane_b32 s2, v251, 5
	v_lshlrev_b32_e32 v3, 5, v135
	v_and_b32_e32 v3, 0xfffffe00, v3
	v_lshl_add_u32 v3, v1, 1, v3
	v_add_u32_e32 v3, s2, v3
	s_waitcnt lgkmcnt(14)
	v_fma_f32 v9, -v8, v137, v9
	v_fma_f32 v10, -v8, v138, v10
	v_fma_f32 v11, -v8, v139, v11
	v_fma_f32 v12, -v8, v140, v12
	v_fma_f32 v13, -v8, v141, v13
	v_fma_f32 v14, -v8, v142, v14
	v_fma_f32 v15, -v8, v143, v15
	v_fma_f32 v16, -v8, v144, v16
	v_fma_f32 v17, -v8, v145, v17
	v_fma_f32 v18, -v8, v146, v18
	v_fma_f32 v19, -v8, v147, v19
	v_fma_f32 v20, -v8, v148, v20
	v_fma_f32 v21, -v8, v149, v21
	v_fma_f32 v22, -v8, v150, v22
	v_fma_f32 v23, -v8, v151, v23
	ds_read_b128 v[136:139], v2 offset:53600
	ds_read_b128 v[140:143], v2 offset:53616
	ds_read_b128 v[144:147], v2 offset:53632
	ds_read_b128 v[148:151], v2 offset:53872
	s_waitcnt lgkmcnt(14)
	v_fma_f32 v10, -v9, v170, v10
	v_fma_f32 v11, -v9, v171, v11
	v_fma_f32 v12, -v9, v172, v12
	v_fma_f32 v13, -v9, v173, v13
	v_fma_f32 v14, -v9, v174, v14
	v_fma_f32 v15, -v9, v175, v15
	v_fma_f32 v16, -v9, v176, v16
	v_fma_f32 v17, -v9, v177, v17
	v_fma_f32 v18, -v9, v178, v18
	v_fma_f32 v19, -v9, v179, v19
	v_fma_f32 v20, -v9, v184, v20
	v_fma_f32 v21, -v9, v185, v21
	v_fma_f32 v22, -v9, v186, v22
	v_fma_f32 v23, -v9, v187, v23
	ds_read_b128 v[168:171], v2 offset:53888
	ds_read_b128 v[172:175], v2 offset:53904
	ds_read_b128 v[176:179], v2 offset:54160
	ds_read_b128 v[184:187], v2 offset:54176
	s_waitcnt lgkmcnt(14)
	v_fma_f32 v11, -v10, v191, v11
	v_fma_f32 v12, -v10, v192, v12
	v_fma_f32 v13, -v10, v193, v13
	v_fma_f32 v14, -v10, v194, v14
	v_fma_f32 v15, -v10, v195, v15
	v_fma_f32 v16, -v10, v196, v16
	v_fma_f32 v17, -v10, v197, v17
	v_fma_f32 v18, -v10, v198, v18
	v_fma_f32 v19, -v10, v199, v19
	v_fma_f32 v20, -v10, v200, v20
	v_fma_f32 v21, -v10, v201, v21
	v_fma_f32 v22, -v10, v202, v22
	v_fma_f32 v23, -v10, v203, v23
	ds_read_b128 v[188:191], v2 offset:54432
	ds_read_b128 v[192:195], v2 offset:54448
	ds_read_b128 v[196:199], v2 offset:54704
	ds_read_b128 v[200:203], v2 offset:54720
	s_waitcnt lgkmcnt(14)
	v_fma_f32 v12, -v11, v234, v12
	v_fma_f32 v13, -v11, v235, v13
	v_fma_f32 v14, -v11, v236, v14
	v_fma_f32 v15, -v11, v237, v15
	v_fma_f32 v16, -v11, v238, v16
	v_fma_f32 v17, -v11, v239, v17
	v_fma_f32 v18, -v11, v240, v18
	v_fma_f32 v19, -v11, v241, v19
	v_fma_f32 v20, -v11, v30, v20
	v_fma_f32 v21, -v11, v31, v21
	v_fma_f32 v22, -v11, v32, v22
	v_fma_f32 v23, -v11, v33, v23
	ds_read_b128 v[234:237], v2 offset:54976
	ds_read_b128 v[238:241], v2 offset:54992
	ds_read_b128 v[30:33], v2 offset:55264
	s_waitcnt lgkmcnt(14)
	v_fma_f32 v13, -v12, v35, v13
	v_fma_f32 v14, -v12, v36, v14
	v_fma_f32 v15, -v12, v37, v15
	v_fma_f32 v16, -v12, v42, v16
	v_fma_f32 v17, -v12, v43, v17
	v_fma_f32 v18, -v12, v44, v18
	v_fma_f32 v19, -v12, v45, v19
	v_fma_f32 v20, -v12, v160, v20
	v_fma_f32 v21, -v12, v161, v21
	v_fma_f32 v22, -v12, v162, v22
	v_fma_f32 v23, -v12, v163, v23
	ds_read_b128 v[34:37], v2 offset:55536
	ds_read_b128 v[42:45], v2 offset:55808
	ds_read_b128 v[160:163], v2 offset:56080
	s_waitcnt lgkmcnt(14)
	v_fma_f32 v14, -v13, v138, v14
	v_fma_f32 v15, -v13, v139, v15
	v_fma_f32 v16, -v13, v140, v16
	v_fma_f32 v17, -v13, v141, v17
	v_fma_f32 v18, -v13, v142, v18
	v_fma_f32 v19, -v13, v143, v19
	v_fma_f32 v20, -v13, v144, v20
	v_fma_f32 v21, -v13, v145, v21
	v_fma_f32 v22, -v13, v146, v22
	v_fma_f32 v23, -v13, v147, v23
	s_waitcnt lgkmcnt(12)
	v_fma_f32 v15, -v14, v151, v15
	v_fma_f32 v16, -v14, v168, v16
	v_fma_f32 v17, -v14, v169, v17
	v_fma_f32 v18, -v14, v170, v18
	v_fma_f32 v19, -v14, v171, v19
	v_fma_f32 v20, -v14, v172, v20
	v_fma_f32 v21, -v14, v173, v21
	v_fma_f32 v22, -v14, v174, v22
	v_fma_f32 v23, -v14, v175, v23
	s_waitcnt lgkmcnt(10)
	v_fma_f32 v16, -v15, v176, v16
	v_fma_f32 v17, -v15, v177, v17
	v_fma_f32 v18, -v15, v178, v18
	v_fma_f32 v19, -v15, v179, v19
	v_fma_f32 v20, -v15, v184, v20
	v_fma_f32 v21, -v15, v185, v21
	v_fma_f32 v22, -v15, v186, v22
	v_fma_f32 v23, -v15, v187, v23
	s_waitcnt lgkmcnt(8)
	v_fma_f32 v17, -v16, v189, v17
	v_fma_f32 v18, -v16, v190, v18
	v_fma_f32 v19, -v16, v191, v19
	v_fma_f32 v20, -v16, v192, v20
	v_fma_f32 v21, -v16, v193, v21
	v_fma_f32 v22, -v16, v194, v22
	v_fma_f32 v23, -v16, v195, v23
	s_waitcnt lgkmcnt(6)
	v_fma_f32 v18, -v17, v198, v18
	v_fma_f32 v19, -v17, v199, v19
	v_fma_f32 v20, -v17, v200, v20
	v_fma_f32 v21, -v17, v201, v21
	v_fma_f32 v22, -v17, v202, v22
	v_fma_f32 v23, -v17, v203, v23
	s_waitcnt lgkmcnt(4)
	v_fma_f32 v19, -v18, v237, v19
	v_fma_f32 v20, -v18, v238, v20
	v_fma_f32 v21, -v18, v239, v21
	v_fma_f32 v22, -v18, v240, v22
	v_fma_f32 v23, -v18, v241, v23
	s_waitcnt lgkmcnt(3)
	v_fma_f32 v20, -v19, v30, v20
	v_fma_f32 v21, -v19, v31, v21
	v_fma_f32 v22, -v19, v32, v22
	v_fma_f32 v23, -v19, v33, v23
	s_waitcnt lgkmcnt(2)
	v_fma_f32 v21, -v20, v35, v21
	v_fma_f32 v22, -v20, v36, v22
	v_fma_f32 v23, -v20, v37, v23
	s_waitcnt lgkmcnt(1)
	v_fma_f32 v22, -v21, v44, v22
	v_fma_f32 v23, -v21, v45, v23
	s_waitcnt lgkmcnt(0)
	v_fma_f32 v23, -v22, v163, v23
	v_cvt_pk_bf16_f32 v8, v8, v8
	v_cvt_pk_bf16_f32 v9, v9, v9
	v_cvt_pk_bf16_f32 v10, v10, v10
	v_cvt_pk_bf16_f32 v11, v11, v11
	v_cvt_pk_bf16_f32 v12, v12, v12
	v_cvt_pk_bf16_f32 v13, v13, v13
	v_cvt_pk_bf16_f32 v14, v14, v14
	v_cvt_pk_bf16_f32 v15, v15, v15
	v_cvt_pk_bf16_f32 v16, v16, v16
	v_cvt_pk_bf16_f32 v17, v17, v17
	v_cvt_pk_bf16_f32 v18, v18, v18
	v_cvt_pk_bf16_f32 v19, v19, v19
	v_cvt_pk_bf16_f32 v20, v20, v20
	v_cvt_pk_bf16_f32 v21, v21, v21
	v_cvt_pk_bf16_f32 v22, v22, v22
	v_cvt_pk_bf16_f32 v23, v23, v23
	ds_write_b16 v3, v8
	ds_write_b16 v3, v9 offset:32
	ds_write_b16 v3, v10 offset:64
	ds_write_b16 v3, v11 offset:96
	ds_write_b16 v3, v12 offset:128
	ds_write_b16 v3, v13 offset:160
	ds_write_b16 v3, v14 offset:192
	ds_write_b16 v3, v15 offset:224
	ds_write_b16 v3, v16 offset:256
	ds_write_b16 v3, v17 offset:288
	ds_write_b16 v3, v18 offset:320
	ds_write_b16 v3, v19 offset:352
	ds_write_b16 v3, v20 offset:384
	ds_write_b16 v3, v21 offset:416
	ds_write_b16 v3, v22 offset:448
	ds_write_b16 v3, v23 offset:480
.Lpd_done:
	s_waitcnt lgkmcnt(0)
	s_barrier
	s_ashr_i32 s6, s24, 6
	v_and_b32_e32 v1, 15, v134
	v_lshrrev_b32_e32 v3, 4, v134
	v_lshlrev_b32_e32 v4, 5, v1
	v_lshl_add_u32 v4, v3, 3, v4
	v_add_u32_e32 v4, 0x1c400, v4
	v_mul_u32_u24_e32 v5, 0x90, v1
	v_lshl_add_u32 v5, v3, 3, v5
	v_add_u32_e32 v5, 0x11000, v5
	v_lshlrev_b32_e32 v7, 4, v3
	v_add_u32_e32 v7, 0x20500, v7
	s_cmp_gt_i32 s6, 3
	s_cbranch_scc1 .Lpe_w
	s_lshl_b32 s1, s6, 6
	v_mul_u32_u24_e32 v6, 0x440, v3
	v_lshl_add_u32 v6, v1, 1, v6
	v_add_u32_e32 v6, s1, v6
	s_lshl_b32 s1, s6, 12
	v_lshl_add_u32 v9, v134, 3, s1
	s_add_u32 s4, s10, s16
	s_addc_u32 s5, s11, s17
	s_add_u32 s4, s4, 0x17800000
	s_addc_u32 s5, s5, 0
	ds_read_b128 v[10:13], v7 offset:256
	ds_read_u16 v14, v6 offset:34816
	ds_read_u16 v15, v6 offset:35088
	ds_read_u16 v16, v6 offset:35360
	ds_read_u16 v17, v6 offset:35632
	ds_read_u16 v18, v6 offset:34848
	ds_read_u16 v19, v6 offset:35120
	ds_read_u16 v20, v6 offset:35392
	ds_read_u16 v21, v6 offset:35664
	ds_read_b64 v[164:165], v4 offset:0
	ds_read_b128 v[22:25], v7 offset:320
	ds_read_u16 v136, v6 offset:39168
	ds_read_u16 v137, v6 offset:39440
	ds_read_u16 v138, v6 offset:39712
	ds_read_u16 v139, v6 offset:39984
	ds_read_u16 v140, v6 offset:39200
	ds_read_u16 v141, v6 offset:39472
	ds_read_u16 v142, v6 offset:39744
	ds_read_u16 v143, v6 offset:40016
	ds_read_b64 v[180:181], v5 offset:2304
	ds_read_b64 v[204:205], v4 offset:512
	s_waitcnt lgkmcnt(11)
	v_lshlrev_b32_e32 v14, 16, v14
	v_lshlrev_b32_e32 v15, 16, v15
	v_lshlrev_b32_e32 v16, 16, v16
	v_lshlrev_b32_e32 v17, 16, v17
	v_lshlrev_b32_e32 v18, 16, v18
	v_lshlrev_b32_e32 v19, 16, v19
	v_lshlrev_b32_e32 v20, 16, v20
	v_lshlrev_b32_e32 v21, 16, v21
	v_mul_f32_e32 v14, v10, v14
	v_mul_f32_e32 v15, v11, v15
	v_mul_f32_e32 v16, v12, v16
	v_mul_f32_e32 v17, v13, v17
	v_mul_f32_e32 v18, v10, v18
	v_mul_f32_e32 v19, v11, v19
	v_mul_f32_e32 v20, v12, v20
	v_mul_f32_e32 v21, v13, v21
	v_cvt_pk_bf16_f32 v246, v14, v15
	v_cvt_pk_bf16_f32 v247, v16, v17
	v_cvt_pk_bf16_f32 v144, v18, v19
	v_cvt_pk_bf16_f32 v145, v20, v21
	v_mfma_f32_16x16x16_bf16 v[14:17], v[164:165], v[246:247], 0
	s_nop 0
	v_mfma_f32_16x16x16_bf16 v[18:21], v[164:165], v[144:145], 0
	ds_read_b128 v[148:151], v7 offset:384
	ds_read_u16 v160, v6 offset:43520
	ds_read_u16 v161, v6 offset:43792
	ds_read_u16 v162, v6 offset:44064
	ds_read_u16 v163, v6 offset:44336
	ds_read_u16 v168, v6 offset:43552
	ds_read_u16 v169, v6 offset:43824
	ds_read_u16 v170, v6 offset:44096
	ds_read_u16 v171, v6 offset:44368
	ds_read_b64 v[146:147], v5 offset:4608
	ds_read_b64 v[172:173], v5 offset:4640
	ds_read_b64 v[174:175], v4 offset:1024
	v_cvt_pk_bf16_f32 v176, v14, v15
	v_cvt_pk_bf16_f32 v177, v16, v17
	global_store_dwordx2 v9, v[176:177], s[4:5] offset:0 nt
	v_cvt_pk_bf16_f32 v178, v18, v19
	v_cvt_pk_bf16_f32 v179, v20, v21
	global_store_dwordx2 v9, v[178:179], s[4:5] offset:2048 nt
	s_waitcnt lgkmcnt(13)
	v_mfma_f32_16x16x16_bf16 v[184:187], v[180:181], v[176:177], 0
	v_mfma_f32_16x16x16_bf16 v[188:191], v[180:181], v[178:179], 0
	s_waitcnt lgkmcnt(12)
	v_lshlrev_b32_e32 v136, 16, v136
	v_lshlrev_b32_e32 v137, 16, v137
	v_lshlrev_b32_e32 v138, 16, v138
	v_lshlrev_b32_e32 v139, 16, v139
	v_lshlrev_b32_e32 v140, 16, v140
	v_lshlrev_b32_e32 v141, 16, v141
	v_lshlrev_b32_e32 v142, 16, v142
	v_lshlrev_b32_e32 v143, 16, v143
	v_mul_f32_e32 v136, v22, v136
	v_mul_f32_e32 v137, v23, v137
	v_mul_f32_e32 v138, v24, v138
	v_mul_f32_e32 v139, v25, v139
	v_mul_f32_e32 v140, v22, v140
	v_mul_f32_e32 v141, v23, v141
	v_mul_f32_e32 v142, v24, v142
	v_mul_f32_e32 v143, v25, v143
	v_sub_f32_e32 v184, v136, v184
	v_sub_f32_e32 v185, v137, v185
	v_sub_f32_e32 v186, v138, v186
	v_sub_f32_e32 v187, v139, v187
	v_cvt_pk_bf16_f32 v246, v184, v185
	v_cvt_pk_bf16_f32 v247, v186, v187
	v_sub_f32_e32 v188, v140, v188
	v_sub_f32_e32 v189, v141, v189
	v_sub_f32_e32 v190, v142, v190
	v_sub_f32_e32 v191, v143, v191
	v_cvt_pk_bf16_f32 v144, v188, v189
	v_cvt_pk_bf16_f32 v145, v190, v191
	v_mfma_f32_16x16x16_bf16 v[184:187], v[204:205], v[246:247], 0
	s_nop 0
	v_mfma_f32_16x16x16_bf16 v[188:191], v[204:205], v[144:145], 0
	ds_read_b128 v[192:195], v7 offset:448
	ds_read_u16 v196, v6 offset:47872
	ds_read_u16 v197, v6 offset:48144
	ds_read_u16 v198, v6 offset:48416
	ds_read_u16 v199, v6 offset:48688
	ds_read_u16 v200, v6 offset:47904
	ds_read_u16 v201, v6 offset:48176
	ds_read_u16 v202, v6 offset:48448
	ds_read_u16 v203, v6 offset:48720
	ds_read_b64 v[164:165], v5 offset:6912
	ds_read_b64 v[180:181], v5 offset:6944
	ds_read_b64 v[234:235], v5 offset:6976
	ds_read_b64 v[236:237], v4 offset:1536
	v_cvt_pk_bf16_f32 v238, v184, v185
	v_cvt_pk_bf16_f32 v239, v186, v187
	global_store_dwordx2 v9, v[238:239], s[4:5] offset:512 nt
	v_cvt_pk_bf16_f32 v240, v188, v189
	v_cvt_pk_bf16_f32 v241, v190, v191
	global_store_dwordx2 v9, v[240:241], s[4:5] offset:2560 nt
	s_waitcnt lgkmcnt(14)
	v_mfma_f32_16x16x16_bf16 v[10:13], v[146:147], v[176:177], 0
	v_mfma_f32_16x16x16_bf16 v[14:17], v[146:147], v[178:179], 0
	v_mfma_f32_16x16x16_bf16 v[10:13], v[172:173], v[238:239], v[10:13]
	v_mfma_f32_16x16x16_bf16 v[14:17], v[172:173], v[240:241], v[14:17]
	s_waitcnt lgkmcnt(13)
	v_lshlrev_b32_e32 v160, 16, v160
	v_lshlrev_b32_e32 v161, 16, v161
	v_lshlrev_b32_e32 v162, 16, v162
	v_lshlrev_b32_e32 v163, 16, v163
	v_lshlrev_b32_e32 v168, 16, v168
	v_lshlrev_b32_e32 v169, 16, v169
	v_lshlrev_b32_e32 v170, 16, v170
	v_lshlrev_b32_e32 v171, 16, v171
	v_mul_f32_e32 v160, v148, v160
	v_mul_f32_e32 v161, v149, v161
	v_mul_f32_e32 v162, v150, v162
	v_mul_f32_e32 v163, v151, v163
	v_mul_f32_e32 v168, v148, v168
	v_mul_f32_e32 v169, v149, v169
	v_mul_f32_e32 v170, v150, v170
	v_mul_f32_e32 v171, v151, v171
	v_sub_f32_e32 v10, v160, v10
	v_sub_f32_e32 v11, v161, v11
	v_sub_f32_e32 v12, v162, v12
	v_sub_f32_e32 v13, v163, v13
	v_cvt_pk_bf16_f32 v246, v10, v11
	v_cvt_pk_bf16_f32 v247, v12, v13
	v_sub_f32_e32 v14, v168, v14
	v_sub_f32_e32 v15, v169, v15
	v_sub_f32_e32 v16, v170, v16
	v_sub_f32_e32 v17, v171, v17
	v_cvt_pk_bf16_f32 v144, v14, v15
	v_cvt_pk_bf16_f32 v145, v16, v17
	v_mfma_f32_16x16x16_bf16 v[10:13], v[174:175], v[246:247], 0
	s_nop 0
	v_mfma_f32_16x16x16_bf16 v[14:17], v[174:175], v[144:145], 0
	s_nop 5
	v_cvt_pk_bf16_f32 v204, v10, v11
	v_cvt_pk_bf16_f32 v205, v12, v13
	global_store_dwordx2 v9, v[204:205], s[4:5] offset:1024 nt
	v_cvt_pk_bf16_f32 v146, v14, v15
	v_cvt_pk_bf16_f32 v147, v16, v17
	global_store_dwordx2 v9, v[146:147], s[4:5] offset:3072 nt
	s_waitcnt lgkmcnt(1)
	v_mfma_f32_16x16x16_bf16 v[18:21], v[164:165], v[176:177], 0
	v_mfma_f32_16x16x16_bf16 v[22:25], v[164:165], v[178:179], 0
	v_mfma_f32_16x16x16_bf16 v[18:21], v[180:181], v[238:239], v[18:21]
	v_mfma_f32_16x16x16_bf16 v[22:25], v[180:181], v[240:241], v[22:25]
	v_mfma_f32_16x16x16_bf16 v[18:21], v[234:235], v[204:205], v[18:21]
	v_mfma_f32_16x16x16_bf16 v[22:25], v[234:235], v[146:147], v[22:25]
	s_waitcnt lgkmcnt(0)
	v_lshlrev_b32_e32 v196, 16, v196
	v_lshlrev_b32_e32 v197, 16, v197
	v_lshlrev_b32_e32 v198, 16, v198
	v_lshlrev_b32_e32 v199, 16, v199
	v_lshlrev_b32_e32 v200, 16, v200
	v_lshlrev_b32_e32 v201, 16, v201
	v_lshlrev_b32_e32 v202, 16, v202
	v_lshlrev_b32_e32 v203, 16, v203
	v_mul_f32_e32 v196, v192, v196
	v_mul_f32_e32 v197, v193, v197
	v_mul_f32_e32 v198, v194, v198
	v_mul_f32_e32 v199, v195, v199
	v_mul_f32_e32 v200, v192, v200
	v_mul_f32_e32 v201, v193, v201
	v_mul_f32_e32 v202, v194, v202
	v_mul_f32_e32 v203, v195, v203
	v_sub_f32_e32 v18, v196, v18
	v_sub_f32_e32 v19, v197, v19
	v_sub_f32_e32 v20, v198, v20
	v_sub_f32_e32 v21, v199, v21
	v_cvt_pk_bf16_f32 v172, v18, v19
	v_cvt_pk_bf16_f32 v173, v20, v21
	v_sub_f32_e32 v22, v200, v22
	v_sub_f32_e32 v23, v201, v23
	v_sub_f32_e32 v24, v202, v24
	v_sub_f32_e32 v25, v203, v25
	v_cvt_pk_bf16_f32 v246, v22, v23
	v_cvt_pk_bf16_f32 v247, v24, v25
	v_mfma_f32_16x16x16_bf16 v[18:21], v[236:237], v[172:173], 0
	s_nop 0
	v_mfma_f32_16x16x16_bf16 v[22:25], v[236:237], v[246:247], 0
	s_nop 5
	v_cvt_pk_bf16_f32 v144, v18, v19
	v_cvt_pk_bf16_f32 v145, v20, v21
	global_store_dwordx2 v9, v[144:145], s[4:5] offset:1536 nt
	v_cvt_pk_bf16_f32 v174, v22, v23
	v_cvt_pk_bf16_f32 v175, v24, v25
	global_store_dwordx2 v9, v[174:175], s[4:5] offset:3584 nt
	s_branch .Lpe_done
